# attention finalize: head-norm gain loads issued at start of exchange block (latency hidden)
# baseline (speedup 1.0000x reference)
; DI void finalize_attn(const Params& p, unsigned char* lds, f32x16 (&o)[8], float l_reg, int lane_k, int wid, bool meta, int qrow0, int hh, int di, float lambda_init, bool dry) {
;     ...
;     if (psub == 0) {
; #pragma unroll
;         for (int d = 0; d < 8; ++d)
; #pragma unroll
;             for (int r = 0; r < 16; ++r) o[d][r] += X[(rg * 128 + d * 16 + r) * 64 + lane];
.LBB0_121:
	v_readlane_b32 s6, v244, 11
	v_readlane_b32 s7, v244, 12
	s_andn2_b64 vcc, exec, s[6:7]
	s_waitcnt lgkmcnt(0)
	s_barrier
	s_cbranch_vccnz .LBB0_77
	v_readlane_b32 s84, v244, 21
	v_readlane_b32 s85, v244, 22
	v_lshlrev_b32_e32 v212, 5, v134
	s_nop 4
	global_load_dwordx4 v[228:231], v212, s[84:85] offset:16
	global_load_dwordx4 v[208:211], v212, s[84:85]
	v_readlane_b32 s6, v244, 34
	s_nop 1
	v_lshl_add_u32 v48, v135, 2, s6
	ds_read2st64_b32 v[150:151], v48 offset1:1
	ds_read2st64_b32 v[152:153], v48 offset0:4 offset1:5
	ds_read2st64_b32 v[154:155], v48 offset0:10 offset1:11
	ds_read2st64_b32 v[156:157], v48 offset0:8 offset1:9
	ds_read2st64_b32 v[158:159], v48 offset0:2 offset1:3
	ds_read2st64_b32 v[160:161], v48 offset0:6 offset1:7
	ds_read2st64_b32 v[162:163], v48 offset0:30 offset1:31
	ds_read2st64_b32 v[164:165], v48 offset0:12 offset1:13
	ds_read2st64_b32 v[166:167], v48 offset0:32 offset1:33
	ds_read2st64_b32 v[168:169], v48 offset0:46 offset1:47
	ds_read2st64_b32 v[170:171], v48 offset0:48 offset1:49
	ds_read2st64_b32 v[172:173], v48 offset0:14 offset1:15
	ds_read2st64_b32 v[174:175], v48 offset0:34 offset1:35
	ds_read2st64_b32 v[200:201], v48 offset0:16 offset1:17
	ds_read2st64_b32 v[202:203], v48 offset0:36 offset1:37
	ds_read2st64_b32 v[204:205], v48 offset0:18 offset1:19
	ds_read2st64_b32 v[206:207], v48 offset0:38 offset1:39
	ds_read2st64_b32 v[216:217], v48 offset0:50 offset1:51
	ds_read2st64_b32 v[218:219], v48 offset0:20 offset1:21
	ds_read2st64_b32 v[220:221], v48 offset0:40 offset1:41
	ds_read2st64_b32 v[222:223], v48 offset0:22 offset1:23
	ds_read2st64_b32 v[232:233], v48 offset0:42 offset1:43
	ds_read2st64_b32 v[234:235], v48 offset0:24 offset1:25
	ds_read2st64_b32 v[236:237], v48 offset0:44 offset1:45
	ds_read2st64_b32 v[238:239], v48 offset0:52 offset1:53
	ds_read2st64_b32 v[240:241], v48 offset0:26 offset1:27
	ds_read2st64_b32 v[242:243], v48 offset0:54 offset1:55
	ds_read2st64_b32 v[248:249], v48 offset0:28 offset1:29
	ds_read2st64_b32 v[250:251], v48 offset0:56 offset1:57
	ds_read2st64_b32 v[252:253], v48 offset0:58 offset1:59
	ds_read2st64_b32 v[254:255], v48 offset0:60 offset1:61
	ds_read2st64_b32 v[226:227], v48 offset0:62 offset1:63
	s_waitcnt lgkmcnt(15)
	v_add_f32_e32 v17, v136, v150
	v_add_f32_e32 v16, v137, v151
	ds_read2st64_b32 v[150:151], v48 offset0:64 offset1:65
	v_add_f32_e32 v47, v118, v152
	v_add_f32_e32 v31, v140, v159
	v_add_f32_e32 v33, v119, v153
	ds_read2st64_b32 v[152:153], v48 offset0:66 offset1:67
	v_add_f32_e32 v32, v138, v158
	v_add_f32_e32 v63, v120, v160
	v_add_f32_e32 v49, v121, v161
	v_add_f32_e32 v65, v122, v156
	v_add_f32_e32 v64, v123, v157
	v_add_f32_e32 v81, v124, v154
	v_add_f32_e32 v80, v125, v155
	ds_read2st64_b32 v[154:155], v48 offset0:68 offset1:69
	ds_read2st64_b32 v[156:157], v48 offset0:70 offset1:71
	ds_read2st64_b32 v[158:159], v48 offset0:72 offset1:73
	ds_read2st64_b32 v[160:161], v48 offset0:74 offset1:75
	v_add_f32_e32 v118, v146, v162
	v_add_f32_e32 v95, v147, v164
	v_add_f32_e32 v94, v94, v165
	v_add_f32_e32 v98, v98, v166
	v_add_f32_e32 v99, v99, v167
	v_add_f32_e32 v82, v82, v170
	v_add_f32_e32 v97, v111, v172
	v_add_f32_e32 v96, v96, v173
	v_add_f32_e32 v100, v100, v174
	v_add_f32_e32 v101, v101, v175
	v_add_f32_e32 v83, v83, v171
	v_add_f32_e32 v112, v114, v200
	v_add_f32_e32 v111, v115, v201
	v_add_f32_e32 v86, v86, v202
	v_add_f32_e32 v87, v87, v203
	v_add_f32_e32 v114, v116, v204
	v_add_f32_e32 v113, v117, v205
	v_add_f32_e32 v88, v88, v206
	v_add_f32_e32 v89, v89, v207
	s_waitcnt lgkmcnt(15)
	v_add_f32_e32 v84, v84, v216
	v_add_f32_e32 v115, v102, v218
	v_add_f32_e32 v102, v103, v219
	v_add_f32_e32 v90, v90, v220
	v_add_f32_e32 v91, v91, v221
	v_add_f32_e32 v85, v85, v217
	v_add_f32_e32 v104, v104, v222
	v_add_f32_e32 v103, v105, v223
	v_add_f32_e32 v92, v92, v232
	v_add_f32_e32 v93, v93, v233
	v_add_f32_e32 v106, v106, v234
	v_add_f32_e32 v105, v107, v235
	s_waitcnt lgkmcnt(13)
	v_add_f32_e32 v70, v70, v238
	v_add_f32_e32 v71, v71, v239
	s_waitcnt lgkmcnt(12)
	v_add_f32_e32 v108, v108, v240
	v_add_f32_e32 v107, v109, v241
	s_waitcnt lgkmcnt(11)
	v_add_f32_e32 v72, v72, v242
	v_add_f32_e32 v73, v73, v243
	s_waitcnt lgkmcnt(10)
	v_add_f32_e32 v109, v144, v249
	v_add_f32_e32 v117, v148, v163
	ds_read2st64_b32 v[162:163], v48 offset0:76 offset1:77
	ds_read2st64_b32 v[164:165], v48 offset0:78 offset1:79
	ds_read2st64_b32 v[166:167], v48 offset0:80 offset1:81
	v_add_f32_e32 v119, v133, v236
	v_add_f32_e32 v120, v141, v237
	s_waitcnt lgkmcnt(12)
	v_add_f32_e32 v74, v74, v250
	v_add_f32_e32 v75, v75, v251
	v_add_f32_e32 v121, v142, v168
	v_add_f32_e32 v122, v145, v169
	ds_read2st64_b32 v[168:169], v48 offset0:82 offset1:83
	ds_read2st64_b32 v[170:171], v48 offset0:84 offset1:85
	ds_read2st64_b32 v[172:173], v48 offset0:86 offset1:87
	ds_read2st64_b32 v[174:175], v48 offset0:88 offset1:89
	ds_read2st64_b32 v[200:201], v48 offset0:90 offset1:91
	ds_read2st64_b32 v[202:203], v48 offset0:92 offset1:93
	ds_read2st64_b32 v[204:205], v48 offset0:94 offset1:95
	ds_read2st64_b32 v[206:207], v48 offset0:96 offset1:97
	ds_read2st64_b32 v[216:217], v48 offset0:98 offset1:99
	ds_read2st64_b32 v[218:219], v48 offset0:100 offset1:101
	ds_read2st64_b32 v[220:221], v48 offset0:102 offset1:103
	ds_read2st64_b32 v[222:223], v48 offset0:104 offset1:105
	ds_read2st64_b32 v[232:233], v48 offset0:106 offset1:107
	ds_read2st64_b32 v[234:235], v48 offset0:108 offset1:109
	ds_read2st64_b32 v[236:237], v48 offset0:110 offset1:111
	ds_read2st64_b32 v[238:239], v48 offset0:112 offset1:113
	ds_read2st64_b32 v[240:241], v48 offset0:114 offset1:115
	ds_read2st64_b32 v[242:243], v48 offset0:116 offset1:117
	v_add_f32_e32 v116, v143, v248
	ds_read2st64_b32 v[248:249], v48 offset0:118 offset1:119
	ds_read2st64_b32 v[250:251], v48 offset0:120 offset1:121
	s_waitcnt lgkmcnt(15)
; DI void finalize_attn(const Params& p, unsigned char* lds, f32x16 (&o)[8], float l_reg, int lane_k, int wid, bool meta, int qrow0, int hh, int di, float lambda_init, bool dry) {
;     ...
;         for (int d = 0; d < 8; ++d)
; #pragma unroll
;             for (int r = 0; r < 16; ++r) o[d][r] += X[(rg * 128 + d * 16 + r) * 64 + lane];
	v_add_f32_e32 v76, v76, v252
	v_add_f32_e32 v77, v77, v253
	ds_read2st64_b32 v[252:253], v48 offset0:122 offset1:123
	v_add_f32_e32 v123, v130, v254
	v_add_f32_e32 v124, v131, v255
	ds_read2st64_b32 v[254:255], v48 offset0:124 offset1:125
	v_add_f32_e32 v125, v132, v226
	v_add_f32_e32 v130, v139, v227
	ds_read2st64_b32 v[226:227], v48 offset0:126 offset1:127
	v_add_f32_e32 v66, v66, v150
	v_add_f32_e32 v67, v67, v151
	v_add_f32_e32 v68, v68, v152
	v_add_f32_e32 v69, v69, v153
	v_add_f32_e32 v54, v54, v154
	v_add_f32_e32 v55, v55, v155
	v_add_f32_e32 v56, v56, v156
	v_add_f32_e32 v57, v57, v157
	v_add_f32_e32 v58, v58, v158
	v_add_f32_e32 v59, v59, v159
	v_add_f32_e32 v60, v60, v160
	v_add_f32_e32 v61, v61, v161
	v_add_f32_e32 v110, v110, v162
	v_add_f32_e32 v126, v126, v163
	v_add_f32_e32 v131, v128, v164
	v_add_f32_e32 v132, v129, v165
	v_add_f32_e32 v128, v50, v166
	v_add_f32_e32 v129, v51, v167
	v_add_f32_e32 v52, v52, v168
	v_add_f32_e32 v53, v53, v169
	v_add_f32_e32 v50, v38, v170
	v_add_f32_e32 v51, v39, v171
	v_add_f32_e32 v40, v40, v172
	v_add_f32_e32 v41, v41, v173
	v_add_f32_e32 v42, v42, v174
	v_add_f32_e32 v43, v43, v175
	v_add_f32_e32 v44, v44, v200
	v_add_f32_e32 v45, v45, v201
	s_waitcnt lgkmcnt(15)
	v_add_f32_e32 v46, v46, v202
	v_add_f32_e32 v62, v62, v203
	v_add_f32_e32 v79, v79, v204
	v_add_f32_e32 v127, v127, v205
	v_add_f32_e32 v38, v34, v206
	v_add_f32_e32 v39, v35, v207
	s_waitcnt lgkmcnt(14)
	v_add_f32_e32 v36, v36, v216
	v_add_f32_e32 v37, v37, v217
	s_waitcnt lgkmcnt(13)
	v_add_f32_e32 v34, v22, v218
	v_add_f32_e32 v35, v23, v219
	s_waitcnt lgkmcnt(12)
	v_add_f32_e32 v24, v24, v220
	v_add_f32_e32 v25, v25, v221
	s_waitcnt lgkmcnt(11)
	v_add_f32_e32 v26, v26, v222
	v_add_f32_e32 v27, v27, v223
	s_waitcnt lgkmcnt(10)
	v_add_f32_e32 v28, v28, v232
	v_add_f32_e32 v29, v29, v233
	s_waitcnt lgkmcnt(9)
	v_add_f32_e32 v30, v30, v234
	v_add_f32_e32 v133, v14, v235
	s_waitcnt lgkmcnt(8)
	v_add_f32_e32 v22, v15, v236
	v_add_f32_e32 v23, v78, v237
	s_waitcnt lgkmcnt(7)
	v_add_f32_e32 v18, v18, v238
	v_add_f32_e32 v19, v19, v239
	s_waitcnt lgkmcnt(6)
	v_add_f32_e32 v20, v20, v240
	v_add_f32_e32 v21, v21, v241
	s_waitcnt lgkmcnt(5)
	v_add_f32_e32 v14, v6, v242
	v_add_f32_e32 v15, v7, v243
	s_waitcnt lgkmcnt(4)
	v_add_f32_e32 v8, v8, v248
	v_add_f32_e32 v9, v9, v249
	s_waitcnt lgkmcnt(3)
	v_add_f32_e32 v10, v10, v250
	v_add_f32_e32 v11, v11, v251
	s_waitcnt lgkmcnt(2)
	v_add_f32_e32 v12, v12, v252
	v_add_f32_e32 v13, v13, v253
	s_waitcnt lgkmcnt(1)
	v_add_f32_e32 v6, v2, v254
	v_add_f32_e32 v7, v3, v255
	s_waitcnt lgkmcnt(0)
; DI float half_sum(float v) { v += SWZ_XOR(v, 1); v += SWZ_XOR(v, 2); v += SWZ_XOR(v, 4); v += SWZ_XOR(v, 8); v += SWZ_XOR(v, 16); return v; }
; DI int crow(int r, int hi) { return (r & 3) + 8 * (r >> 2) + 4 * hi; }
; DI void finalize_attn(const Params& p, unsigned char* lds, f32x16 (&o)[8], float l_reg, int lane_k, int wid, bool meta, int qrow0, int hh, int di, float lambda_init, bool dry) {
;     ...
;         for (int d = 0; d < 8; ++d)
; #pragma unroll
;             for (int r = 0; r < 16; ++r) R[crow(r, hi) * 256 + 32 * d + r32] = o[d][r];
;         asm volatile("s_waitcnt lgkmcnt(0)" ::: "memory");
;         const float og = 1.f - misc[1]; const int c8 = (lane & 31) * 8;
;         const f32x4 g0 = *(const f32x4*)(p.diff_gn + (size_t)di * 256 + c8) * og, g1 = *(const f32x4*)(p.diff_gn + (size_t)di * 256 + c8 + 4) * og;
;         bf16_t* dstb = qbuf + (size_t)(qrow0 + 32 * rg + (lane >> 5)) * 2048 + hh * 256 + c8;
;         const int nrow = dry ? 0 : (meta ? (rg == 0 ? 16 : 0) : 32);
; #pragma unroll 2
;         for (int it = 0; it < 16; ++it) {
;             const int row = 2 * it + (lane >> 5);
;             f32x4 a = *(const f32x4*)(R + row * 256 + c8), b = *(const f32x4*)(R + row * 256 + c8 + 4);
;             float ss = a[0] * a[0] + a[1] * a[1] + a[2] * a[2] + a[3] * a[3] + b[0] * b[0] + b[1] * b[1] + b[2] * b[2] + b[3] * b[3];
;             ss = half_sum(ss);
;             const float rstd = rsqrtf(ss * (1.f / 256.f) + 1e-6f);
;             a = a * rstd * g0; b = b * rstd * g1;
	v_add_f32_e32 v2, v4, v226
	v_add_f32_e32 v3, v5, v227
	v_lshlrev_b32_e32 v4, 12, v0
	v_lshlrev_b32_e32 v5, 2, v134
	v_add3_u32 v4, s6, v4, v5
	ds_write2_b32 v4, v17, v112 offset1:32
	v_add_u32_e32 v5, 0x400, v4
	v_add_u32_e32 v17, 0xc00, v4
	ds_write2_b32 v5, v16, v111 offset1:32
	v_add_u32_e32 v16, 0x800, v4
	ds_write2_b32 v17, v31, v113 offset1:32
	v_add_u32_e32 v31, 0x2000, v4
	ds_write2_b32 v16, v32, v114 offset1:32
	ds_write2_b32 v31, v47, v115 offset1:32
	v_add_u32_e32 v32, 0x2400, v4
	v_add_u32_e32 v47, 0x2c00, v4
	ds_write2_b32 v32, v33, v102 offset1:32
	v_add_u32_e32 v33, 0x2800, v4
	ds_write2_b32 v47, v49, v103 offset1:32
	v_add_u32_e32 v49, 0x4400, v4
	ds_write2_b32 v33, v63, v104 offset1:32
	v_add_u32_e32 v48, 0x4000, v4
	ds_write2_b32 v49, v64, v105 offset1:32
	v_add_u32_e32 v63, 0x4800, v4
	v_add_u32_e32 v64, 0x4c00, v4
	ds_write2_b32 v48, v65, v106 offset1:32
	ds_write2_b32 v63, v81, v108 offset1:32
	ds_write2_b32 v64, v80, v107 offset1:32
	v_add_u32_e32 v65, 0x6000, v4
	v_add_u32_e32 v78, 0x6400, v4
	v_add_u32_e32 v80, 0x6800, v4
	v_add_u32_e32 v81, 0x6c00, v4
	ds_write2_b32 v65, v95, v116 offset1:32
	ds_write2_b32 v78, v94, v109 offset1:32
	ds_write2_b32 v80, v97, v118 offset1:32
	ds_write2_b32 v81, v96, v117 offset1:32
	ds_write2_b32 v4, v98, v82 offset0:64 offset1:96
	ds_write2_b32 v5, v99, v83 offset0:64 offset1:96
	ds_write2_b32 v16, v100, v84 offset0:64 offset1:96
	ds_write2_b32 v17, v101, v85 offset0:64 offset1:96
	ds_write2_b32 v31, v86, v70 offset0:64 offset1:96
	ds_write2_b32 v32, v87, v71 offset0:64 offset1:96
	ds_write2_b32 v33, v88, v72 offset0:64 offset1:96
	ds_write2_b32 v47, v89, v73 offset0:64 offset1:96
	ds_write2_b32 v48, v90, v74 offset0:64 offset1:96
	ds_write2_b32 v49, v91, v75 offset0:64 offset1:96
	ds_write2_b32 v63, v92, v76 offset0:64 offset1:96
	ds_write2_b32 v64, v93, v77 offset0:64 offset1:96
	ds_write2_b32 v65, v119, v123 offset0:64 offset1:96
	ds_write2_b32 v78, v120, v124 offset0:64 offset1:96
	ds_write2_b32 v80, v121, v125 offset0:64 offset1:96
	ds_write2_b32 v81, v122, v130 offset0:64 offset1:96
	ds_write2_b32 v4, v66, v128 offset0:128 offset1:160
	ds_write2_b32 v5, v67, v129 offset0:128 offset1:160
	ds_write2_b32 v16, v68, v52 offset0:128 offset1:160
	ds_write2_b32 v17, v69, v53 offset0:128 offset1:160
	ds_write2_b32 v31, v54, v50 offset0:128 offset1:160
	ds_write2_b32 v32, v55, v51 offset0:128 offset1:160
	ds_write2_b32 v33, v56, v40 offset0:128 offset1:160
	ds_write2_b32 v47, v57, v41 offset0:128 offset1:160
	ds_write2_b32 v48, v58, v42 offset0:128 offset1:160
	ds_write2_b32 v49, v59, v43 offset0:128 offset1:160
	ds_write2_b32 v63, v60, v44 offset0:128 offset1:160
	ds_write2_b32 v64, v61, v45 offset0:128 offset1:160
	ds_write2_b32 v65, v110, v46 offset0:128 offset1:160
	ds_write2_b32 v78, v126, v62 offset0:128 offset1:160
	ds_write2_b32 v80, v131, v79 offset0:128 offset1:160
	ds_write2_b32 v81, v132, v127 offset0:128 offset1:160
	ds_write2_b32 v4, v38, v18 offset0:192 offset1:224
	ds_write2_b32 v5, v39, v19 offset0:192 offset1:224
	ds_write2_b32 v16, v36, v20 offset0:192 offset1:224
	ds_write2_b32 v17, v37, v21 offset0:192 offset1:224
	ds_write2_b32 v31, v34, v14 offset0:192 offset1:224
	ds_write2_b32 v32, v35, v15 offset0:192 offset1:224
	ds_write2_b32 v33, v24, v8 offset0:192 offset1:224
	ds_write2_b32 v47, v25, v9 offset0:192 offset1:224
	ds_write2_b32 v48, v26, v10 offset0:192 offset1:224
	ds_write2_b32 v49, v27, v11 offset0:192 offset1:224
	ds_write2_b32 v63, v28, v12 offset0:192 offset1:224
	ds_write2_b32 v64, v29, v13 offset0:192 offset1:224
	ds_write2_b32 v65, v30, v6 offset0:192 offset1:224
	ds_write2_b32 v78, v133, v7 offset0:192 offset1:224
	ds_write2_b32 v80, v22, v2 offset0:192 offset1:224
	ds_write2_b32 v81, v23, v3 offset0:192 offset1:224
	v_readlane_b32 s6, v245, 17
	s_waitcnt lgkmcnt(0)
	v_lshlrev_b32_e32 v18, 5, v134
	s_nop 0
	v_mov_b32_e32 v2, s6
	ds_read_b32 v2, v2
	v_readlane_b32 s6, v244, 21
	v_readlane_b32 s7, v244, 22
	s_waitcnt lgkmcnt(0)
	v_sub_f32_e32 v16, 1.0, v2
	s_nop 2
	s_and_b64 s[6:7], s[76:77], exec
	v_readlane_b32 s7, v244, 36
	v_readlane_b32 s6, v244, 35
	s_cselect_b32 s6, s6, 32
	s_waitcnt vmcnt(1)
	v_pk_mul_f32 v[14:15], v[230:231], v[16:17] op_sel_hi:[1,0]
	s_waitcnt vmcnt(0)
	v_pk_mul_f32 v[10:11], v[210:211], v[16:17] op_sel_hi:[1,0]
	v_pk_mul_f32 v[12:13], v[208:209], v[16:17] op_sel_hi:[1,0]
	v_pk_mul_f32 v[16:17], v[228:229], v[16:17] op_sel_hi:[1,0]
	v_lshl_or_b32 v2, v0, 10, v18
	v_add_u32_e32 v20, s7, v2
	v_readlane_b32 s7, v244, 32
	s_add_i32 s7, s7, s71
	s_nop 0
	v_add_u32_e32 v2, s7, v0
	v_ashrrev_i32_e32 v3, 31, v2
	v_readlane_b32 s7, v244, 37
	v_lshlrev_b64 v[2:3], 12, v[2:3]
	s_add_u32 s8, s7, s78
	v_readlane_b32 s7, v244, 38
	v_lshl_or_b32 v2, v134, 4, v2
	s_addc_u32 s9, s7, s79
	v_lshl_add_u64 v[18:19], s[8:9], 0, v[2:3]
	s_mov_b32 s7, 0
	s_branch .LBB0_124
